# lgkmcnt ladder + k0-first ds_read order in P2 and P8 K-loops (pure scheduling)
# baseline (speedup 1.0000x reference)
.LBB0_157:
	v_add_u32_e32 v140, s91, v180
	ds_read_b128 v[128:131], v140
	ds_read_b128 v[136:139], v140 offset:2048
	ds_read_b128 v[132:135], v140 offset:1024
	ds_read_b128 v[140:143], v140 offset:3072
	s_add_u32 s10, s8, 0xfff80080
	s_addc_u32 s11, s9, -1
	s_cmp_eq_u32 s74, 28
	s_cselect_b32 s73, s2, s11
	s_cselect_b32 s72, s13, s10
	s_cselect_b32 s11, s20, s71
	s_cselect_b32 s10, s63, s65
	v_lshl_add_u64 v[232:233], s[8:9], 0, v[166:167]
	s_add_i32 m0, s40, 0xc000
	ds_read_b128 v[144:147], v208
	ds_read_b128 v[176:179], v208 offset:2048
	ds_read_b128 v[216:219], v208 offset:4096
	ds_read_b128 v[224:227], v208 offset:6144
	ds_read_b128 v[172:175], v208 offset:1024
	ds_read_b128 v[212:215], v208 offset:3072
	ds_read_b128 v[220:223], v208 offset:5120
	ds_read_b128 v[228:231], v208 offset:7168
	global_load_lds_dwordx4 v[232:233], off
	v_lshl_add_u64 v[232:233], s[8:9], 0, v[168:169]
	s_add_i32 m0, s40, 0xe000
	s_nop 0
	global_load_lds_dwordx4 v[232:233], off
	s_waitcnt lgkmcnt(8)
	s_barrier
	s_setprio 1
	s_waitcnt lgkmcnt(7)
	v_mfma_f32_16x16x32_bf16 v[124:127], v[128:131], v[144:147], v[124:127]
	v_mfma_f32_16x16x32_bf16 v[120:123], v[136:139], v[144:147], v[120:123]
	s_waitcnt lgkmcnt(6)
	v_mfma_f32_16x16x32_bf16 v[108:111], v[128:131], v[176:179], v[108:111]
	v_mfma_f32_16x16x32_bf16 v[104:107], v[136:139], v[176:179], v[104:107]
	s_waitcnt lgkmcnt(5)
	v_mfma_f32_16x16x32_bf16 v[92:95], v[128:131], v[216:219], v[92:95]
	v_mfma_f32_16x16x32_bf16 v[88:91], v[136:139], v[216:219], v[88:91]
	s_waitcnt lgkmcnt(4)
	v_mfma_f32_16x16x32_bf16 v[76:79], v[128:131], v[224:227], v[76:79]
	v_mfma_f32_16x16x32_bf16 v[72:75], v[136:139], v[224:227], v[72:75]
	s_waitcnt lgkmcnt(3)
	v_mfma_f32_16x16x32_bf16 v[124:127], v[132:135], v[172:175], v[124:127]
	v_mfma_f32_16x16x32_bf16 v[120:123], v[140:143], v[172:175], v[120:123]
	s_waitcnt lgkmcnt(2)
	v_mfma_f32_16x16x32_bf16 v[108:111], v[132:135], v[212:215], v[108:111]
	v_mfma_f32_16x16x32_bf16 v[104:107], v[140:143], v[212:215], v[104:107]
	s_waitcnt lgkmcnt(1)
	v_mfma_f32_16x16x32_bf16 v[92:95], v[132:135], v[220:223], v[92:95]
	v_mfma_f32_16x16x32_bf16 v[88:91], v[140:143], v[220:223], v[88:91]
	s_waitcnt lgkmcnt(0)
	v_mfma_f32_16x16x32_bf16 v[76:79], v[132:135], v[228:231], v[76:79]
	v_mfma_f32_16x16x32_bf16 v[72:75], v[140:143], v[228:231], v[72:75]
	s_setprio 0
	s_barrier
	s_add_i32 s34, s91, s39
	v_add_u32_e32 v156, s92, v180
	v_lshl_add_u64 v[248:249], s[10:11], 0, v[150:151]
	s_mov_b32 m0, s34
	ds_read_b128 v[232:235], v156
	ds_read_b128 v[240:243], v156 offset:2048
	ds_read_b128 v[236:239], v156 offset:1024
	ds_read_b128 v[244:247], v156 offset:3072
	global_load_lds_dwordx4 v[248:249], off
	v_lshl_add_u64 v[250:251], s[10:11], 0, v[154:155]
	s_add_i32 m0, s34, 0x2000
	s_nop 0
	global_load_lds_dwordx4 v[250:251], off
	s_barrier
	s_setprio 1
	s_waitcnt lgkmcnt(2)
	v_mfma_f32_16x16x32_bf16 v[116:119], v[232:235], v[144:147], v[116:119]
	v_mfma_f32_16x16x32_bf16 v[112:115], v[240:243], v[144:147], v[112:115]
	v_mfma_f32_16x16x32_bf16 v[100:103], v[232:235], v[176:179], v[100:103]
	v_mfma_f32_16x16x32_bf16 v[96:99], v[240:243], v[176:179], v[96:99]
	v_mfma_f32_16x16x32_bf16 v[84:87], v[232:235], v[216:219], v[84:87]
	v_mfma_f32_16x16x32_bf16 v[80:83], v[240:243], v[216:219], v[80:83]
	v_mfma_f32_16x16x32_bf16 v[68:71], v[232:235], v[224:227], v[68:71]
	v_mfma_f32_16x16x32_bf16 v[64:67], v[240:243], v[224:227], v[64:67]
	s_waitcnt lgkmcnt(0)
	v_mfma_f32_16x16x32_bf16 v[116:119], v[236:239], v[172:175], v[116:119]
	v_mfma_f32_16x16x32_bf16 v[112:115], v[244:247], v[172:175], v[112:115]
	v_mfma_f32_16x16x32_bf16 v[100:103], v[236:239], v[212:215], v[100:103]
	v_mfma_f32_16x16x32_bf16 v[96:99], v[244:247], v[212:215], v[96:99]
	v_mfma_f32_16x16x32_bf16 v[84:87], v[236:239], v[220:223], v[84:87]
	v_mfma_f32_16x16x32_bf16 v[80:83], v[244:247], v[220:223], v[80:83]
	v_mfma_f32_16x16x32_bf16 v[68:71], v[236:239], v[228:231], v[68:71]
	v_mfma_f32_16x16x32_bf16 v[64:67], v[244:247], v[228:231], v[64:67]
	s_setprio 0
	s_mov_b32 m0, s40
	v_lshl_add_u64 v[252:253], s[72:73], 0, v[148:149]
	s_barrier
	ds_read_b128 v[144:147], v208 offset:16384
	ds_read_b128 v[176:179], v208 offset:18432
	ds_read_b128 v[216:219], v208 offset:20480
	ds_read_b128 v[224:227], v208 offset:22528
	ds_read_b128 v[172:175], v208 offset:17408
	ds_read_b128 v[212:215], v208 offset:19456
	ds_read_b128 v[220:223], v208 offset:21504
	ds_read_b128 v[228:231], v208 offset:23552
	global_load_lds_dwordx4 v[252:253], off
	v_lshl_add_u64 v[182:183], s[72:73], 0, v[152:153]
	s_mov_b32 m0, s41
	s_nop 0
	global_load_lds_dwordx4 v[182:183], off
	s_barrier
	s_setprio 1
	s_waitcnt lgkmcnt(7)
	v_mfma_f32_16x16x32_bf16 v[60:63], v[128:131], v[144:147], v[60:63]
	v_mfma_f32_16x16x32_bf16 v[56:59], v[136:139], v[144:147], v[56:59]
	s_waitcnt lgkmcnt(6)
	v_mfma_f32_16x16x32_bf16 v[44:47], v[128:131], v[176:179], v[44:47]
	v_mfma_f32_16x16x32_bf16 v[40:43], v[136:139], v[176:179], v[40:43]
	s_waitcnt lgkmcnt(5)
	v_mfma_f32_16x16x32_bf16 v[28:31], v[128:131], v[216:219], v[28:31]
	v_mfma_f32_16x16x32_bf16 v[24:27], v[136:139], v[216:219], v[24:27]
	s_waitcnt lgkmcnt(4)
	v_mfma_f32_16x16x32_bf16 v[12:15], v[128:131], v[224:227], v[12:15]
	v_mfma_f32_16x16x32_bf16 v[8:11], v[136:139], v[224:227], v[8:11]
	s_waitcnt lgkmcnt(3)
	v_mfma_f32_16x16x32_bf16 v[60:63], v[132:135], v[172:175], v[60:63]
	v_mfma_f32_16x16x32_bf16 v[56:59], v[140:143], v[172:175], v[56:59]
	s_waitcnt lgkmcnt(2)
	v_mfma_f32_16x16x32_bf16 v[44:47], v[132:135], v[212:215], v[44:47]
	v_mfma_f32_16x16x32_bf16 v[40:43], v[140:143], v[212:215], v[40:43]
	s_waitcnt lgkmcnt(1)
	v_mfma_f32_16x16x32_bf16 v[28:31], v[132:135], v[220:223], v[28:31]
	v_mfma_f32_16x16x32_bf16 v[24:27], v[140:143], v[220:223], v[24:27]
	s_waitcnt lgkmcnt(0)
	v_mfma_f32_16x16x32_bf16 v[12:15], v[132:135], v[228:231], v[12:15]
	v_mfma_f32_16x16x32_bf16 v[8:11], v[140:143], v[228:231], v[8:11]
	s_setprio 0
	s_barrier
	s_add_u32 s34, s10, 0x80000
	s_addc_u32 s35, s11, 0
	s_add_i32 s75, s92, s39
	v_lshl_add_u64 v[128:129], s[34:35], 0, v[150:151]
	s_mov_b32 m0, s75
	s_nop 0
	global_load_lds_dwordx4 v[128:129], off
	v_lshl_add_u64 v[128:129], s[34:35], 0, v[154:155]
	s_add_i32 m0, s75, 0x2000
	s_nop 0
	global_load_lds_dwordx4 v[128:129], off
	s_waitcnt vmcnt(6)
	s_barrier
	s_setprio 1
	v_mfma_f32_16x16x32_bf16 v[52:55], v[232:235], v[144:147], v[52:55]
	v_mfma_f32_16x16x32_bf16 v[48:51], v[240:243], v[144:147], v[48:51]
	v_mfma_f32_16x16x32_bf16 v[36:39], v[232:235], v[176:179], v[36:39]
	v_mfma_f32_16x16x32_bf16 v[32:35], v[240:243], v[176:179], v[32:35]
	v_mfma_f32_16x16x32_bf16 v[20:23], v[232:235], v[216:219], v[20:23]
	v_mfma_f32_16x16x32_bf16 v[16:19], v[240:243], v[216:219], v[16:19]
	v_mfma_f32_16x16x32_bf16 v[4:7], v[232:235], v[224:227], v[4:7]
	v_mfma_f32_16x16x32_bf16 v[0:3], v[240:243], v[224:227], v[0:3]
	v_mfma_f32_16x16x32_bf16 v[52:55], v[236:239], v[172:175], v[52:55]
	v_mfma_f32_16x16x32_bf16 v[48:51], v[244:247], v[172:175], v[48:51]
	v_mfma_f32_16x16x32_bf16 v[36:39], v[236:239], v[212:215], v[36:39]
	v_mfma_f32_16x16x32_bf16 v[32:35], v[244:247], v[212:215], v[32:35]
	v_mfma_f32_16x16x32_bf16 v[20:23], v[236:239], v[220:223], v[20:23]
	v_mfma_f32_16x16x32_bf16 v[16:19], v[244:247], v[220:223], v[16:19]
	v_mfma_f32_16x16x32_bf16 v[4:7], v[236:239], v[228:231], v[4:7]
	v_mfma_f32_16x16x32_bf16 v[0:3], v[244:247], v[228:231], v[0:3]
	s_setprio 0
	s_add_i32 s75, 0, 0x18000
	v_add_u32_e32 v140, s75, v180
	s_barrier
	ds_read_b128 v[128:131], v140
	ds_read_b128 v[136:139], v140 offset:2048
	ds_read_b128 v[132:135], v140 offset:1024
	ds_read_b128 v[140:143], v140 offset:3072
	s_add_u32 s34, s72, 0x80000
	s_addc_u32 s35, s73, 0
	s_mov_b32 m0, s82
	v_lshl_add_u64 v[232:233], s[34:35], 0, v[148:149]
	ds_read_b128 v[144:147], v208 offset:32768
	ds_read_b128 v[176:179], v208 offset:34816
	ds_read_b128 v[216:219], v208 offset:36864
	ds_read_b128 v[224:227], v208 offset:38912
	ds_read_b128 v[172:175], v208 offset:33792
	ds_read_b128 v[212:215], v208 offset:35840
	ds_read_b128 v[220:223], v208 offset:37888
	ds_read_b128 v[228:231], v208 offset:39936
	global_load_lds_dwordx4 v[232:233], off
	v_lshl_add_u64 v[232:233], s[34:35], 0, v[152:153]
	s_mov_b32 m0, s83
	s_nop 0
	global_load_lds_dwordx4 v[232:233], off
	s_waitcnt lgkmcnt(8)
	s_barrier
	s_setprio 1
	s_waitcnt lgkmcnt(7)
	v_mfma_f32_16x16x32_bf16 v[124:127], v[128:131], v[144:147], v[124:127]
	v_mfma_f32_16x16x32_bf16 v[120:123], v[136:139], v[144:147], v[120:123]
	s_waitcnt lgkmcnt(6)
	v_mfma_f32_16x16x32_bf16 v[108:111], v[128:131], v[176:179], v[108:111]
	v_mfma_f32_16x16x32_bf16 v[104:107], v[136:139], v[176:179], v[104:107]
	s_waitcnt lgkmcnt(5)
	v_mfma_f32_16x16x32_bf16 v[92:95], v[128:131], v[216:219], v[92:95]
	v_mfma_f32_16x16x32_bf16 v[88:91], v[136:139], v[216:219], v[88:91]
	s_waitcnt lgkmcnt(4)
	v_mfma_f32_16x16x32_bf16 v[76:79], v[128:131], v[224:227], v[76:79]
	v_mfma_f32_16x16x32_bf16 v[72:75], v[136:139], v[224:227], v[72:75]
	s_waitcnt lgkmcnt(3)
	v_mfma_f32_16x16x32_bf16 v[124:127], v[132:135], v[172:175], v[124:127]
	v_mfma_f32_16x16x32_bf16 v[120:123], v[140:143], v[172:175], v[120:123]
	s_waitcnt lgkmcnt(2)
	v_mfma_f32_16x16x32_bf16 v[108:111], v[132:135], v[212:215], v[108:111]
	v_mfma_f32_16x16x32_bf16 v[104:107], v[140:143], v[212:215], v[104:107]
	s_waitcnt lgkmcnt(1)
	v_mfma_f32_16x16x32_bf16 v[92:95], v[132:135], v[220:223], v[92:95]
	v_mfma_f32_16x16x32_bf16 v[88:91], v[140:143], v[220:223], v[88:91]
	s_waitcnt lgkmcnt(0)
	v_mfma_f32_16x16x32_bf16 v[76:79], v[132:135], v[228:231], v[76:79]
	v_mfma_f32_16x16x32_bf16 v[72:75], v[140:143], v[228:231], v[72:75]
	s_setprio 0
	s_barrier
	s_add_i32 s34, 0, 0x1c000
	s_add_i32 s35, s75, s39
	v_add_u32_e32 v156, s34, v180
	v_lshl_add_u64 v[248:249], v[248:249], 0, s[58:59]
	s_mov_b32 m0, s35
	ds_read_b128 v[232:235], v156
	ds_read_b128 v[240:243], v156 offset:2048
	ds_read_b128 v[236:239], v156 offset:1024
	ds_read_b128 v[244:247], v156 offset:3072
	global_load_lds_dwordx4 v[248:249], off
	v_lshl_add_u64 v[248:249], v[250:251], 0, s[58:59]
	s_add_i32 m0, s35, 0x2000
	s_nop 0
	global_load_lds_dwordx4 v[248:249], off
	s_barrier
	s_setprio 1
	s_waitcnt lgkmcnt(2)
	v_mfma_f32_16x16x32_bf16 v[116:119], v[232:235], v[144:147], v[116:119]
	v_mfma_f32_16x16x32_bf16 v[112:115], v[240:243], v[144:147], v[112:115]
	v_mfma_f32_16x16x32_bf16 v[100:103], v[232:235], v[176:179], v[100:103]
	v_mfma_f32_16x16x32_bf16 v[96:99], v[240:243], v[176:179], v[96:99]
	v_mfma_f32_16x16x32_bf16 v[84:87], v[232:235], v[216:219], v[84:87]
	v_mfma_f32_16x16x32_bf16 v[80:83], v[240:243], v[216:219], v[80:83]
	v_mfma_f32_16x16x32_bf16 v[68:71], v[232:235], v[224:227], v[68:71]
	v_mfma_f32_16x16x32_bf16 v[64:67], v[240:243], v[224:227], v[64:67]
	s_waitcnt lgkmcnt(0)
	v_mfma_f32_16x16x32_bf16 v[116:119], v[236:239], v[172:175], v[116:119]
	v_mfma_f32_16x16x32_bf16 v[112:115], v[244:247], v[172:175], v[112:115]
	v_mfma_f32_16x16x32_bf16 v[100:103], v[236:239], v[212:215], v[100:103]
	v_mfma_f32_16x16x32_bf16 v[96:99], v[244:247], v[212:215], v[96:99]
	v_mfma_f32_16x16x32_bf16 v[84:87], v[236:239], v[220:223], v[84:87]
	v_mfma_f32_16x16x32_bf16 v[80:83], v[244:247], v[220:223], v[80:83]
	v_mfma_f32_16x16x32_bf16 v[68:71], v[236:239], v[228:231], v[68:71]
	v_mfma_f32_16x16x32_bf16 v[64:67], v[244:247], v[228:231], v[64:67]
	s_setprio 0
	s_mov_b32 m0, s87
	v_lshl_add_u64 v[248:249], v[252:253], 0, s[58:59]
	s_barrier
	ds_read_b128 v[144:147], v208 offset:49152
	ds_read_b128 v[176:179], v208 offset:51200
	ds_read_b128 v[216:219], v208 offset:53248
	ds_read_b128 v[224:227], v208 offset:55296
	ds_read_b128 v[172:175], v208 offset:50176
	ds_read_b128 v[212:215], v208 offset:52224
	ds_read_b128 v[220:223], v208 offset:54272
	ds_read_b128 v[228:231], v208 offset:56320
	global_load_lds_dwordx4 v[248:249], off
	v_lshl_add_u64 v[182:183], v[182:183], 0, s[58:59]
	s_mov_b32 m0, s88
	s_nop 0
	global_load_lds_dwordx4 v[182:183], off
	s_barrier
	s_setprio 1
	s_waitcnt lgkmcnt(7)
	v_mfma_f32_16x16x32_bf16 v[60:63], v[128:131], v[144:147], v[60:63]
	v_mfma_f32_16x16x32_bf16 v[56:59], v[136:139], v[144:147], v[56:59]
	s_waitcnt lgkmcnt(6)
	v_mfma_f32_16x16x32_bf16 v[44:47], v[128:131], v[176:179], v[44:47]
	v_mfma_f32_16x16x32_bf16 v[40:43], v[136:139], v[176:179], v[40:43]
	s_waitcnt lgkmcnt(5)
	v_mfma_f32_16x16x32_bf16 v[28:31], v[128:131], v[216:219], v[28:31]
	v_mfma_f32_16x16x32_bf16 v[24:27], v[136:139], v[216:219], v[24:27]
	s_waitcnt lgkmcnt(4)
	v_mfma_f32_16x16x32_bf16 v[12:15], v[128:131], v[224:227], v[12:15]
	v_mfma_f32_16x16x32_bf16 v[8:11], v[136:139], v[224:227], v[8:11]
	s_waitcnt lgkmcnt(3)
	v_mfma_f32_16x16x32_bf16 v[60:63], v[132:135], v[172:175], v[60:63]
	v_mfma_f32_16x16x32_bf16 v[56:59], v[140:143], v[172:175], v[56:59]
	s_waitcnt lgkmcnt(2)
	v_mfma_f32_16x16x32_bf16 v[44:47], v[132:135], v[212:215], v[44:47]
	v_mfma_f32_16x16x32_bf16 v[40:43], v[140:143], v[212:215], v[40:43]
	s_waitcnt lgkmcnt(1)
	v_mfma_f32_16x16x32_bf16 v[28:31], v[132:135], v[220:223], v[28:31]
	v_mfma_f32_16x16x32_bf16 v[24:27], v[140:143], v[220:223], v[24:27]
	s_waitcnt lgkmcnt(0)
	v_mfma_f32_16x16x32_bf16 v[12:15], v[132:135], v[228:231], v[12:15]
	v_mfma_f32_16x16x32_bf16 v[8:11], v[140:143], v[228:231], v[8:11]
	s_setprio 0
	s_barrier
	s_add_u32 s10, s10, 0x80080
	s_addc_u32 s11, s11, 0
	s_add_i32 s34, s34, s39
	v_lshl_add_u64 v[128:129], s[10:11], 0, v[150:151]
	s_mov_b32 m0, s34
	s_nop 0
	global_load_lds_dwordx4 v[128:129], off
	v_lshl_add_u64 v[128:129], s[10:11], 0, v[154:155]
	s_add_i32 m0, s34, 0x2000
	s_nop 0
	global_load_lds_dwordx4 v[128:129], off
	s_waitcnt vmcnt(6)
	s_barrier
	s_setprio 1
	v_mfma_f32_16x16x32_bf16 v[52:55], v[232:235], v[144:147], v[52:55]
	v_mfma_f32_16x16x32_bf16 v[48:51], v[240:243], v[144:147], v[48:51]
	v_mfma_f32_16x16x32_bf16 v[36:39], v[232:235], v[176:179], v[36:39]
	v_mfma_f32_16x16x32_bf16 v[32:35], v[240:243], v[176:179], v[32:35]
	v_mfma_f32_16x16x32_bf16 v[20:23], v[232:235], v[216:219], v[20:23]
	v_mfma_f32_16x16x32_bf16 v[16:19], v[240:243], v[216:219], v[16:19]
	v_mfma_f32_16x16x32_bf16 v[4:7], v[232:235], v[224:227], v[4:7]
	v_mfma_f32_16x16x32_bf16 v[0:3], v[240:243], v[224:227], v[0:3]
	v_mfma_f32_16x16x32_bf16 v[52:55], v[236:239], v[172:175], v[52:55]
	v_mfma_f32_16x16x32_bf16 v[48:51], v[244:247], v[172:175], v[48:51]
	v_mfma_f32_16x16x32_bf16 v[36:39], v[236:239], v[212:215], v[36:39]
	v_mfma_f32_16x16x32_bf16 v[32:35], v[244:247], v[212:215], v[32:35]
	v_mfma_f32_16x16x32_bf16 v[20:23], v[236:239], v[220:223], v[20:23]
	v_mfma_f32_16x16x32_bf16 v[16:19], v[244:247], v[220:223], v[16:19]
	v_mfma_f32_16x16x32_bf16 v[4:7], v[236:239], v[228:231], v[4:7]
	v_mfma_f32_16x16x32_bf16 v[0:3], v[244:247], v[228:231], v[0:3]
	s_setprio 0
	s_add_i32 s74, s74, 2
	s_add_u32 s8, s8, 0x100
	s_addc_u32 s9, s9, 0
	s_add_u32 s65, s65, 0x100
	s_addc_u32 s71, s71, 0
	s_cmp_gt_u32 s74, 29
	s_barrier
	s_cbranch_scc0 .LBB0_157
	s_cmp_gt_i32 s70, 15
	s_cselect_b64 s[74:75], -1, 0
	s_cmp_lt_i32 s70, 16
	s_cselect_b64 s[72:73], -1, 0
	s_cmp_gt_i32 s12, 9
	s_mov_b64 s[8:9], -1
	s_cbranch_scc0 .LBB0_338
	s_cmp_gt_u32 s12, 11
	s_cbranch_scc0 .LBB0_272
	s_cmp_gt_u32 s12, 19
	s_mov_b64 s[80:81], -1
	s_cbranch_scc0 .LBB0_173
	s_cmp_gt_u32 s12, 27
	s_cbranch_scc0 .LBB0_170
	s_lshl_b32 s2, s12, 8
	s_cmp_gt_u32 s12, 35
	s_mov_b64 s[8:9], -1
	s_mov_b64 s[78:79], -1
	s_cbranch_scc0 .LBB0_168
	s_cmp_gt_u32 s12, 43
	s_mov_b64 s[10:11], -1
	s_cbranch_scc0 .LBB0_165
	s_add_i32 s20, s2, 0xffffd400
	s_mov_b64 s[10:11], 0

.LBB0_1065:
	ds_read_b128 v[152:155], v148
	ds_read_b128 v[160:163], v148 offset:2048
	ds_read_b128 v[156:159], v148 offset:1024
	ds_read_b128 v[164:167], v148 offset:3072
	s_add_u32 s28, s26, 0xfff80080
	s_addc_u32 s29, s27, -1
	s_cmp_eq_u32 s59, 28
	s_cselect_b32 s31, s15, s29
	s_cselect_b32 s30, s25, s28
	s_cselect_b32 s29, s17, s58
	s_cselect_b32 s28, s56, s57
	v_lshl_add_u64 v[144:145], s[26:27], 0, v[138:139]
	s_add_i32 m0, s47, 0xc000
	ds_read_b128 v[168:171], v149
	ds_read_b128 v[176:179], v149 offset:2048
	ds_read_b128 v[186:189], v149 offset:4096
	ds_read_b128 v[194:197], v149 offset:6144
	ds_read_b128 v[172:175], v149 offset:1024
	ds_read_b128 v[180:183], v149 offset:3072
	ds_read_b128 v[190:193], v149 offset:5120
	ds_read_b128 v[198:201], v149 offset:7168
	global_load_lds_dwordx4 v[144:145], off
	v_lshl_add_u64 v[144:145], s[26:27], 0, v[140:141]
	s_add_i32 m0, s47, 0xe000
	s_nop 0
	global_load_lds_dwordx4 v[144:145], off
	s_waitcnt lgkmcnt(8)
	s_barrier
	s_setprio 1
	s_waitcnt lgkmcnt(7)
	v_mfma_f32_16x16x32_bf16 v[124:127], v[152:155], v[168:171], v[124:127]
	v_mfma_f32_16x16x32_bf16 v[120:123], v[160:163], v[168:171], v[120:123]
	s_waitcnt lgkmcnt(6)
	v_mfma_f32_16x16x32_bf16 v[108:111], v[152:155], v[176:179], v[108:111]
	v_mfma_f32_16x16x32_bf16 v[104:107], v[160:163], v[176:179], v[104:107]
	s_waitcnt lgkmcnt(5)
	v_mfma_f32_16x16x32_bf16 v[92:95], v[152:155], v[186:189], v[92:95]
	v_mfma_f32_16x16x32_bf16 v[88:91], v[160:163], v[186:189], v[88:91]
	s_waitcnt lgkmcnt(4)
	v_mfma_f32_16x16x32_bf16 v[76:79], v[152:155], v[194:197], v[76:79]
	v_mfma_f32_16x16x32_bf16 v[72:75], v[160:163], v[194:197], v[72:75]
	s_waitcnt lgkmcnt(3)
	v_mfma_f32_16x16x32_bf16 v[124:127], v[156:159], v[172:175], v[124:127]
	v_mfma_f32_16x16x32_bf16 v[120:123], v[164:167], v[172:175], v[120:123]
	s_waitcnt lgkmcnt(2)
	v_mfma_f32_16x16x32_bf16 v[108:111], v[156:159], v[180:183], v[108:111]
	v_mfma_f32_16x16x32_bf16 v[104:107], v[164:167], v[180:183], v[104:107]
	s_waitcnt lgkmcnt(1)
	v_mfma_f32_16x16x32_bf16 v[92:95], v[156:159], v[190:193], v[92:95]
	v_mfma_f32_16x16x32_bf16 v[88:91], v[164:167], v[190:193], v[88:91]
	s_waitcnt lgkmcnt(0)
	v_mfma_f32_16x16x32_bf16 v[76:79], v[156:159], v[198:201], v[76:79]
	v_mfma_f32_16x16x32_bf16 v[72:75], v[164:167], v[198:201], v[72:75]
	s_setprio 0
	s_barrier
	s_add_i32 s34, s53, s40
	v_lshl_add_u64 v[144:145], s[28:29], 0, v[132:133]
	s_mov_b32 m0, s34
	ds_read_b128 v[202:205], v150
	ds_read_b128 v[210:213], v150 offset:2048
	ds_read_b128 v[206:209], v150 offset:1024
	ds_read_b128 v[214:217], v150 offset:3072
	global_load_lds_dwordx4 v[144:145], off
	v_lshl_add_u64 v[218:219], s[28:29], 0, v[128:129]
	s_add_i32 m0, s34, 0x2000
	s_nop 0
	global_load_lds_dwordx4 v[218:219], off
	s_barrier
	s_setprio 1
	s_waitcnt lgkmcnt(2)
	v_mfma_f32_16x16x32_bf16 v[116:119], v[202:205], v[168:171], v[116:119]
	v_mfma_f32_16x16x32_bf16 v[112:115], v[210:213], v[168:171], v[112:115]
	v_mfma_f32_16x16x32_bf16 v[100:103], v[202:205], v[176:179], v[100:103]
	v_mfma_f32_16x16x32_bf16 v[96:99], v[210:213], v[176:179], v[96:99]
	v_mfma_f32_16x16x32_bf16 v[84:87], v[202:205], v[186:189], v[84:87]
	v_mfma_f32_16x16x32_bf16 v[80:83], v[210:213], v[186:189], v[80:83]
	v_mfma_f32_16x16x32_bf16 v[68:71], v[202:205], v[194:197], v[68:71]
	v_mfma_f32_16x16x32_bf16 v[64:67], v[210:213], v[194:197], v[64:67]
	s_waitcnt lgkmcnt(0)
	v_mfma_f32_16x16x32_bf16 v[116:119], v[206:209], v[172:175], v[116:119]
	v_mfma_f32_16x16x32_bf16 v[112:115], v[214:217], v[172:175], v[112:115]
	v_mfma_f32_16x16x32_bf16 v[100:103], v[206:209], v[180:183], v[100:103]
	v_mfma_f32_16x16x32_bf16 v[96:99], v[214:217], v[180:183], v[96:99]
	v_mfma_f32_16x16x32_bf16 v[84:87], v[206:209], v[190:193], v[84:87]
	v_mfma_f32_16x16x32_bf16 v[80:83], v[214:217], v[190:193], v[80:83]
	v_mfma_f32_16x16x32_bf16 v[68:71], v[206:209], v[198:201], v[68:71]
	v_mfma_f32_16x16x32_bf16 v[64:67], v[214:217], v[198:201], v[64:67]
	s_setprio 0
	s_mov_b32 m0, s47
	v_lshl_add_u64 v[220:221], s[30:31], 0, v[134:135]
	s_barrier
	ds_read_b128 v[168:171], v149 offset:16384
	ds_read_b128 v[176:179], v149 offset:18432
	ds_read_b128 v[186:189], v149 offset:20480
	ds_read_b128 v[194:197], v149 offset:22528
	ds_read_b128 v[172:175], v149 offset:17408
	ds_read_b128 v[180:183], v149 offset:19456
	ds_read_b128 v[190:193], v149 offset:21504
	ds_read_b128 v[198:201], v149 offset:23552
	global_load_lds_dwordx4 v[220:221], off
	v_lshl_add_u64 v[222:223], s[30:31], 0, v[130:131]
	s_mov_b32 m0, s48
	s_nop 0
	global_load_lds_dwordx4 v[222:223], off
	s_barrier
	s_setprio 1
	s_waitcnt lgkmcnt(7)
	v_mfma_f32_16x16x32_bf16 v[60:63], v[152:155], v[168:171], v[60:63]
	v_mfma_f32_16x16x32_bf16 v[56:59], v[160:163], v[168:171], v[56:59]
	s_waitcnt lgkmcnt(6)
	v_mfma_f32_16x16x32_bf16 v[44:47], v[152:155], v[176:179], v[44:47]
	v_mfma_f32_16x16x32_bf16 v[40:43], v[160:163], v[176:179], v[40:43]
	s_waitcnt lgkmcnt(5)
	v_mfma_f32_16x16x32_bf16 v[28:31], v[152:155], v[186:189], v[28:31]
	v_mfma_f32_16x16x32_bf16 v[24:27], v[160:163], v[186:189], v[24:27]
	s_waitcnt lgkmcnt(4)
	v_mfma_f32_16x16x32_bf16 v[12:15], v[152:155], v[194:197], v[12:15]
	v_mfma_f32_16x16x32_bf16 v[8:11], v[160:163], v[194:197], v[8:11]
	s_waitcnt lgkmcnt(3)
	v_mfma_f32_16x16x32_bf16 v[60:63], v[156:159], v[172:175], v[60:63]
	v_mfma_f32_16x16x32_bf16 v[56:59], v[164:167], v[172:175], v[56:59]
	s_waitcnt lgkmcnt(2)
	v_mfma_f32_16x16x32_bf16 v[44:47], v[156:159], v[180:183], v[44:47]
	v_mfma_f32_16x16x32_bf16 v[40:43], v[164:167], v[180:183], v[40:43]
	s_waitcnt lgkmcnt(1)
	v_mfma_f32_16x16x32_bf16 v[28:31], v[156:159], v[190:193], v[28:31]
	v_mfma_f32_16x16x32_bf16 v[24:27], v[164:167], v[190:193], v[24:27]
	s_waitcnt lgkmcnt(0)
	v_mfma_f32_16x16x32_bf16 v[12:15], v[156:159], v[198:201], v[12:15]
	v_mfma_f32_16x16x32_bf16 v[8:11], v[164:167], v[198:201], v[8:11]
	s_setprio 0
	s_barrier
	s_add_u32 s34, s28, 0x80000
	s_addc_u32 s35, s29, 0
	s_add_i32 s60, s54, s40
	v_lshl_add_u64 v[152:153], s[34:35], 0, v[132:133]
	s_mov_b32 m0, s60
	s_nop 0
	global_load_lds_dwordx4 v[152:153], off
	v_lshl_add_u64 v[152:153], s[34:35], 0, v[128:129]
	s_add_i32 m0, s60, 0x2000
	s_nop 0
	global_load_lds_dwordx4 v[152:153], off
	s_waitcnt vmcnt(6)
	s_barrier
	s_setprio 1
	v_mfma_f32_16x16x32_bf16 v[52:55], v[202:205], v[168:171], v[52:55]
	v_mfma_f32_16x16x32_bf16 v[48:51], v[210:213], v[168:171], v[48:51]
	v_mfma_f32_16x16x32_bf16 v[36:39], v[202:205], v[176:179], v[36:39]
	v_mfma_f32_16x16x32_bf16 v[32:35], v[210:213], v[176:179], v[32:35]
	v_mfma_f32_16x16x32_bf16 v[20:23], v[202:205], v[186:189], v[20:23]
	v_mfma_f32_16x16x32_bf16 v[16:19], v[210:213], v[186:189], v[16:19]
	v_mfma_f32_16x16x32_bf16 v[4:7], v[202:205], v[194:197], v[4:7]
	v_mfma_f32_16x16x32_bf16 v[0:3], v[210:213], v[194:197], v[0:3]
	v_mfma_f32_16x16x32_bf16 v[52:55], v[206:209], v[172:175], v[52:55]
	v_mfma_f32_16x16x32_bf16 v[48:51], v[214:217], v[172:175], v[48:51]
	v_mfma_f32_16x16x32_bf16 v[36:39], v[206:209], v[180:183], v[36:39]
	v_mfma_f32_16x16x32_bf16 v[32:35], v[214:217], v[180:183], v[32:35]
	v_mfma_f32_16x16x32_bf16 v[20:23], v[206:209], v[190:193], v[20:23]
	v_mfma_f32_16x16x32_bf16 v[16:19], v[214:217], v[190:193], v[16:19]
	v_mfma_f32_16x16x32_bf16 v[4:7], v[206:209], v[198:201], v[4:7]
	v_mfma_f32_16x16x32_bf16 v[0:3], v[214:217], v[198:201], v[0:3]
	s_setprio 0
	s_add_i32 s34, 0, 0x18000
	v_add_u32_e32 v151, s34, v147
	s_barrier
	ds_read_b128 v[152:155], v151
	ds_read_b128 v[160:163], v151 offset:2048
	ds_read_b128 v[156:159], v151 offset:1024
	ds_read_b128 v[164:167], v151 offset:3072
	s_add_u32 s30, s30, 0x80000
	s_addc_u32 s31, s31, 0
	s_mov_b32 m0, s49
	v_lshl_add_u64 v[202:203], s[30:31], 0, v[134:135]
	ds_read_b128 v[168:171], v149 offset:32768
	ds_read_b128 v[176:179], v149 offset:34816
	ds_read_b128 v[186:189], v149 offset:36864
	ds_read_b128 v[194:197], v149 offset:38912
	ds_read_b128 v[172:175], v149 offset:33792
	ds_read_b128 v[180:183], v149 offset:35840
	ds_read_b128 v[190:193], v149 offset:37888
	ds_read_b128 v[198:201], v149 offset:39936
	global_load_lds_dwordx4 v[202:203], off
	v_lshl_add_u64 v[202:203], s[30:31], 0, v[130:131]
	s_mov_b32 m0, s50
	s_nop 0
	global_load_lds_dwordx4 v[202:203], off
	s_waitcnt lgkmcnt(8)
	s_barrier
	s_setprio 1
	s_waitcnt lgkmcnt(7)
	v_mfma_f32_16x16x32_bf16 v[124:127], v[152:155], v[168:171], v[124:127]
	v_mfma_f32_16x16x32_bf16 v[120:123], v[160:163], v[168:171], v[120:123]
	s_waitcnt lgkmcnt(6)
	v_mfma_f32_16x16x32_bf16 v[108:111], v[152:155], v[176:179], v[108:111]
	v_mfma_f32_16x16x32_bf16 v[104:107], v[160:163], v[176:179], v[104:107]
	s_waitcnt lgkmcnt(5)
	v_mfma_f32_16x16x32_bf16 v[92:95], v[152:155], v[186:189], v[92:95]
	v_mfma_f32_16x16x32_bf16 v[88:91], v[160:163], v[186:189], v[88:91]
	s_waitcnt lgkmcnt(4)
	v_mfma_f32_16x16x32_bf16 v[76:79], v[152:155], v[194:197], v[76:79]
	v_mfma_f32_16x16x32_bf16 v[72:75], v[160:163], v[194:197], v[72:75]
	s_waitcnt lgkmcnt(3)
	v_mfma_f32_16x16x32_bf16 v[124:127], v[156:159], v[172:175], v[124:127]
	v_mfma_f32_16x16x32_bf16 v[120:123], v[164:167], v[172:175], v[120:123]
	s_waitcnt lgkmcnt(2)
	v_mfma_f32_16x16x32_bf16 v[108:111], v[156:159], v[180:183], v[108:111]
	v_mfma_f32_16x16x32_bf16 v[104:107], v[164:167], v[180:183], v[104:107]
	s_waitcnt lgkmcnt(1)
	v_mfma_f32_16x16x32_bf16 v[92:95], v[156:159], v[190:193], v[92:95]
	v_mfma_f32_16x16x32_bf16 v[88:91], v[164:167], v[190:193], v[88:91]
	s_waitcnt lgkmcnt(0)
	v_mfma_f32_16x16x32_bf16 v[76:79], v[156:159], v[198:201], v[76:79]
	v_mfma_f32_16x16x32_bf16 v[72:75], v[164:167], v[198:201], v[72:75]
	s_setprio 0
	s_barrier
	s_add_i32 s30, 0, 0x1c000
	s_add_i32 s31, s34, s40
	v_add_u32_e32 v151, s30, v147
	v_lshl_add_u64 v[144:145], v[144:145], 0, s[10:11]
	s_mov_b32 m0, s31
	ds_read_b128 v[202:205], v151
	ds_read_b128 v[210:213], v151 offset:2048
	ds_read_b128 v[206:209], v151 offset:1024
	ds_read_b128 v[214:217], v151 offset:3072
	global_load_lds_dwordx4 v[144:145], off
	v_lshl_add_u64 v[144:145], v[218:219], 0, s[10:11]
	s_add_i32 m0, s31, 0x2000
	s_nop 0
	global_load_lds_dwordx4 v[144:145], off
	s_barrier
	s_setprio 1
	s_waitcnt lgkmcnt(2)
	v_mfma_f32_16x16x32_bf16 v[116:119], v[202:205], v[168:171], v[116:119]
	v_mfma_f32_16x16x32_bf16 v[112:115], v[210:213], v[168:171], v[112:115]
	v_mfma_f32_16x16x32_bf16 v[100:103], v[202:205], v[176:179], v[100:103]
	v_mfma_f32_16x16x32_bf16 v[96:99], v[210:213], v[176:179], v[96:99]
	v_mfma_f32_16x16x32_bf16 v[84:87], v[202:205], v[186:189], v[84:87]
	v_mfma_f32_16x16x32_bf16 v[80:83], v[210:213], v[186:189], v[80:83]
	v_mfma_f32_16x16x32_bf16 v[68:71], v[202:205], v[194:197], v[68:71]
	v_mfma_f32_16x16x32_bf16 v[64:67], v[210:213], v[194:197], v[64:67]
	s_waitcnt lgkmcnt(0)
	v_mfma_f32_16x16x32_bf16 v[116:119], v[206:209], v[172:175], v[116:119]
	v_mfma_f32_16x16x32_bf16 v[112:115], v[214:217], v[172:175], v[112:115]
	v_mfma_f32_16x16x32_bf16 v[100:103], v[206:209], v[180:183], v[100:103]
	v_mfma_f32_16x16x32_bf16 v[96:99], v[214:217], v[180:183], v[96:99]
	v_mfma_f32_16x16x32_bf16 v[84:87], v[206:209], v[190:193], v[84:87]
	v_mfma_f32_16x16x32_bf16 v[80:83], v[214:217], v[190:193], v[80:83]
	v_mfma_f32_16x16x32_bf16 v[68:71], v[206:209], v[198:201], v[68:71]
	v_mfma_f32_16x16x32_bf16 v[64:67], v[214:217], v[198:201], v[64:67]
	s_setprio 0
	s_mov_b32 m0, s51
	v_lshl_add_u64 v[144:145], v[220:221], 0, s[10:11]
	s_barrier
	ds_read_b128 v[168:171], v149 offset:49152
	ds_read_b128 v[176:179], v149 offset:51200
	ds_read_b128 v[186:189], v149 offset:53248
	ds_read_b128 v[194:197], v149 offset:55296
	ds_read_b128 v[172:175], v149 offset:50176
	ds_read_b128 v[180:183], v149 offset:52224
	ds_read_b128 v[190:193], v149 offset:54272
	ds_read_b128 v[198:201], v149 offset:56320
	global_load_lds_dwordx4 v[144:145], off
	v_lshl_add_u64 v[144:145], v[222:223], 0, s[10:11]
	s_mov_b32 m0, s52
	s_nop 0
	global_load_lds_dwordx4 v[144:145], off
	s_barrier
	s_setprio 1
	s_waitcnt lgkmcnt(7)
	v_mfma_f32_16x16x32_bf16 v[60:63], v[152:155], v[168:171], v[60:63]
	v_mfma_f32_16x16x32_bf16 v[56:59], v[160:163], v[168:171], v[56:59]
	s_waitcnt lgkmcnt(6)
	v_mfma_f32_16x16x32_bf16 v[44:47], v[152:155], v[176:179], v[44:47]
	v_mfma_f32_16x16x32_bf16 v[40:43], v[160:163], v[176:179], v[40:43]
	s_waitcnt lgkmcnt(5)
	v_mfma_f32_16x16x32_bf16 v[28:31], v[152:155], v[186:189], v[28:31]
	v_mfma_f32_16x16x32_bf16 v[24:27], v[160:163], v[186:189], v[24:27]
	s_waitcnt lgkmcnt(4)
	v_mfma_f32_16x16x32_bf16 v[12:15], v[152:155], v[194:197], v[12:15]
	v_mfma_f32_16x16x32_bf16 v[8:11], v[160:163], v[194:197], v[8:11]
	s_waitcnt lgkmcnt(3)
	v_mfma_f32_16x16x32_bf16 v[60:63], v[156:159], v[172:175], v[60:63]
	v_mfma_f32_16x16x32_bf16 v[56:59], v[164:167], v[172:175], v[56:59]
	s_waitcnt lgkmcnt(2)
	v_mfma_f32_16x16x32_bf16 v[44:47], v[156:159], v[180:183], v[44:47]
	v_mfma_f32_16x16x32_bf16 v[40:43], v[164:167], v[180:183], v[40:43]
	s_waitcnt lgkmcnt(1)
	v_mfma_f32_16x16x32_bf16 v[28:31], v[156:159], v[190:193], v[28:31]
	v_mfma_f32_16x16x32_bf16 v[24:27], v[164:167], v[190:193], v[24:27]
	s_waitcnt lgkmcnt(0)
	v_mfma_f32_16x16x32_bf16 v[12:15], v[156:159], v[198:201], v[12:15]
	v_mfma_f32_16x16x32_bf16 v[8:11], v[164:167], v[198:201], v[8:11]
	s_setprio 0
	s_barrier
	s_add_u32 s28, s28, 0x80080
	s_addc_u32 s29, s29, 0
	s_add_i32 s30, s30, s40
	v_lshl_add_u64 v[144:145], s[28:29], 0, v[132:133]
	s_mov_b32 m0, s30
	s_nop 0
	global_load_lds_dwordx4 v[144:145], off
	v_lshl_add_u64 v[144:145], s[28:29], 0, v[128:129]
	s_add_i32 m0, s30, 0x2000
	s_nop 0
	global_load_lds_dwordx4 v[144:145], off
	s_waitcnt vmcnt(6)
	s_barrier
	s_setprio 1
	v_mfma_f32_16x16x32_bf16 v[52:55], v[202:205], v[168:171], v[52:55]
	v_mfma_f32_16x16x32_bf16 v[48:51], v[210:213], v[168:171], v[48:51]
	v_mfma_f32_16x16x32_bf16 v[36:39], v[202:205], v[176:179], v[36:39]
	v_mfma_f32_16x16x32_bf16 v[32:35], v[210:213], v[176:179], v[32:35]
	v_mfma_f32_16x16x32_bf16 v[20:23], v[202:205], v[186:189], v[20:23]
	v_mfma_f32_16x16x32_bf16 v[16:19], v[210:213], v[186:189], v[16:19]
	v_mfma_f32_16x16x32_bf16 v[4:7], v[202:205], v[194:197], v[4:7]
	v_mfma_f32_16x16x32_bf16 v[0:3], v[210:213], v[194:197], v[0:3]
	v_mfma_f32_16x16x32_bf16 v[52:55], v[206:209], v[172:175], v[52:55]
	v_mfma_f32_16x16x32_bf16 v[48:51], v[214:217], v[172:175], v[48:51]
	v_mfma_f32_16x16x32_bf16 v[36:39], v[206:209], v[180:183], v[36:39]
	v_mfma_f32_16x16x32_bf16 v[32:35], v[214:217], v[180:183], v[32:35]
	v_mfma_f32_16x16x32_bf16 v[20:23], v[206:209], v[190:193], v[20:23]
	v_mfma_f32_16x16x32_bf16 v[16:19], v[214:217], v[190:193], v[16:19]
	v_mfma_f32_16x16x32_bf16 v[4:7], v[206:209], v[198:201], v[4:7]
	v_mfma_f32_16x16x32_bf16 v[0:3], v[214:217], v[198:201], v[0:3]
	s_setprio 0
	s_add_i32 s59, s59, 2
	s_add_u32 s26, s26, 0x100
	s_addc_u32 s27, s27, 0
	s_add_u32 s57, s57, 0x100
	s_addc_u32 s58, s58, 0
	s_cmp_gt_u32 s59, 29
	s_barrier
	s_cbranch_scc0 .LBB0_1065
	v_mul_f32_e32 v154, 0xbfb8aa3b, v124
	v_exp_f32_e32 v154, v154
	v_mul_f32_e32 v155, 0xbfb8aa3b, v125
	v_exp_f32_e32 v155, v155
	v_lshl_add_u32 v151, s24, 8, v146
	v_add_f32_e32 v154, 1.0, v154
	v_rcp_f32_e32 v154, v154
	v_add_f32_e32 v155, 1.0, v155
	v_rcp_f32_e32 v155, v155
	s_lshl_b32 s24, s13, 7
	v_mul_f32_e32 v124, v124, v154
	v_mul_f32_e32 v120, v120, v124
	v_mul_f32_e32 v124, v125, v155
	v_mul_f32_e32 v125, 0xbfb8aa3b, v126
	v_exp_f32_e32 v125, v125
	v_mul_f32_e32 v154, 0xbfb8aa3b, v127
	v_exp_f32_e32 v154, v154
	v_mul_f32_e32 v121, v121, v124
	v_add_f32_e32 v124, 1.0, v125
	v_rcp_f32_e32 v124, v124
	v_add_f32_e32 v125, 1.0, v154
	v_rcp_f32_e32 v125, v125
	v_cvt_pk_bf16_f32 v120, v120, v121
	v_mul_f32_e32 v121, v126, v124
	v_mul_f32_e32 v121, v122, v121
	v_mul_f32_e32 v122, v127, v125
	v_mul_f32_e32 v122, v123, v122
	v_mul_f32_e32 v123, 0xbfb8aa3b, v116
	v_exp_f32_e32 v123, v123
	v_mul_f32_e32 v124, 0xbfb8aa3b, v117
	v_exp_f32_e32 v124, v124
	v_cvt_pk_bf16_f32 v121, v121, v122
	v_add_f32_e32 v122, 1.0, v123
	v_rcp_f32_e32 v122, v122
	v_add_f32_e32 v123, 1.0, v124
	s_ashr_i32 s25, s24, 31
	v_mov_b64_e32 v[144:145], s[6:7]
	v_rcp_f32_e32 v123, v123
	v_mad_i64_i32 v[152:153], s[26:27], v151, s55, v[144:145]
	s_lshl_b64 s[24:25], s[24:25], 1
	v_lshl_add_u64 v[152:153], v[152:153], 0, s[24:25]
	s_mov_b32 s13, s9
	v_lshl_add_u64 v[152:153], v[152:153], 0, s[12:13]
	v_mul_f32_e32 v116, v116, v122
	v_lshl_add_u64 v[152:153], v[152:153], 0, v[136:137]
	v_mul_f32_e32 v112, v112, v116
	v_mul_f32_e32 v116, v117, v123
	v_mul_f32_e32 v117, 0xbfb8aa3b, v118
	global_store_dwordx2 v[152:153], v[120:121], off
	v_exp_f32_e32 v117, v117
	v_mul_f32_e32 v120, 0xbfb8aa3b, v119
	v_exp_f32_e32 v120, v120
	v_mul_f32_e32 v113, v113, v116
	v_add_f32_e32 v116, 1.0, v117
	v_rcp_f32_e32 v116, v116
	v_add_f32_e32 v117, 1.0, v120
	v_rcp_f32_e32 v117, v117
	v_cvt_pk_bf16_f32 v112, v112, v113
	v_mul_f32_e32 v113, v118, v116
	v_mul_f32_e32 v113, v114, v113
	v_mul_f32_e32 v114, v119, v117
	v_mul_f32_e32 v114, v115, v114
	v_cvt_pk_bf16_f32 v113, v113, v114
	v_mul_f32_e32 v114, 0xbfb8aa3b, v108
	v_exp_f32_e32 v114, v114
	v_mul_f32_e32 v115, 0xbfb8aa3b, v109
	v_exp_f32_e32 v115, v115
	global_store_dwordx2 v[152:153], v[112:113], off offset:128
	v_add_f32_e32 v114, 1.0, v114
	v_rcp_f32_e32 v114, v114
	v_add_f32_e32 v115, 1.0, v115
	v_rcp_f32_e32 v115, v115
	v_or_b32_e32 v112, 16, v151
	v_mul_f32_e32 v108, v108, v114
	v_mul_f32_e32 v104, v104, v108
	v_mul_f32_e32 v108, v109, v115
	v_mul_f32_e32 v109, 0xbfb8aa3b, v110
	v_exp_f32_e32 v109, v109
	v_mul_f32_e32 v114, 0xbfb8aa3b, v111
	v_exp_f32_e32 v114, v114
	v_mul_f32_e32 v105, v105, v108
	v_add_f32_e32 v108, 1.0, v109
	v_rcp_f32_e32 v108, v108
	v_add_f32_e32 v109, 1.0, v114
	v_rcp_f32_e32 v109, v109
	v_cvt_pk_bf16_f32 v104, v104, v105
	v_mul_f32_e32 v105, v110, v108
	v_mul_f32_e32 v105, v106, v105
	v_mul_f32_e32 v106, v111, v109
	v_mul_f32_e32 v106, v107, v106
	v_mul_f32_e32 v107, 0xbfb8aa3b, v100
	v_exp_f32_e32 v107, v107
	v_mul_f32_e32 v108, 0xbfb8aa3b, v101
	v_exp_f32_e32 v108, v108
	v_cvt_pk_bf16_f32 v105, v105, v106
	v_add_f32_e32 v106, 1.0, v107
	v_rcp_f32_e32 v106, v106
	v_add_f32_e32 v107, 1.0, v108
	v_rcp_f32_e32 v107, v107
	v_mad_i64_i32 v[112:113], s[26:27], v112, s55, v[144:145]
	v_lshl_add_u64 v[112:113], v[112:113], 0, s[24:25]
	v_lshl_add_u64 v[112:113], v[112:113], 0, s[12:13]
	v_mul_f32_e32 v100, v100, v106
	v_lshl_add_u64 v[112:113], v[112:113], 0, v[136:137]
	v_mul_f32_e32 v96, v96, v100
	v_mul_f32_e32 v100, v101, v107
	v_mul_f32_e32 v101, 0xbfb8aa3b, v102
	global_store_dwordx2 v[112:113], v[104:105], off
	v_exp_f32_e32 v101, v101
	v_mul_f32_e32 v104, 0xbfb8aa3b, v103
	v_exp_f32_e32 v104, v104
	v_mul_f32_e32 v97, v97, v100
	v_add_f32_e32 v100, 1.0, v101
	v_rcp_f32_e32 v100, v100
	v_add_f32_e32 v101, 1.0, v104
	v_rcp_f32_e32 v101, v101
	v_cvt_pk_bf16_f32 v96, v96, v97
	v_mul_f32_e32 v97, v102, v100
	v_mul_f32_e32 v97, v98, v97
	v_mul_f32_e32 v98, v103, v101
	v_mul_f32_e32 v98, v99, v98
	v_cvt_pk_bf16_f32 v97, v97, v98
	v_mul_f32_e32 v98, 0xbfb8aa3b, v92
	v_exp_f32_e32 v98, v98
	v_mul_f32_e32 v99, 0xbfb8aa3b, v93
	v_exp_f32_e32 v99, v99
	global_store_dwordx2 v[112:113], v[96:97], off offset:128
	v_add_f32_e32 v98, 1.0, v98
	v_rcp_f32_e32 v98, v98
	v_add_f32_e32 v99, 1.0, v99
	v_rcp_f32_e32 v99, v99
	v_or_b32_e32 v96, 32, v151
	v_mul_f32_e32 v92, v92, v98
	v_mul_f32_e32 v88, v88, v92
	v_mul_f32_e32 v92, v93, v99
	v_mul_f32_e32 v93, 0xbfb8aa3b, v94
	v_exp_f32_e32 v93, v93
	v_mul_f32_e32 v98, 0xbfb8aa3b, v95
	v_exp_f32_e32 v98, v98
	v_mul_f32_e32 v89, v89, v92
	v_add_f32_e32 v92, 1.0, v93
	v_rcp_f32_e32 v92, v92
	v_add_f32_e32 v93, 1.0, v98
	v_rcp_f32_e32 v93, v93
	v_cvt_pk_bf16_f32 v88, v88, v89
	v_mul_f32_e32 v89, v94, v92
	v_mul_f32_e32 v89, v90, v89
	v_mul_f32_e32 v90, v95, v93
	v_mul_f32_e32 v90, v91, v90
	v_mul_f32_e32 v91, 0xbfb8aa3b, v84
	v_exp_f32_e32 v91, v91
	v_mul_f32_e32 v92, 0xbfb8aa3b, v85
	v_exp_f32_e32 v92, v92
	v_cvt_pk_bf16_f32 v89, v89, v90
	v_add_f32_e32 v90, 1.0, v91
	v_rcp_f32_e32 v90, v90
	v_add_f32_e32 v91, 1.0, v92
	v_rcp_f32_e32 v91, v91
	v_mad_i64_i32 v[96:97], s[26:27], v96, s55, v[144:145]
	v_lshl_add_u64 v[96:97], v[96:97], 0, s[24:25]
	v_lshl_add_u64 v[96:97], v[96:97], 0, s[12:13]
	v_mul_f32_e32 v84, v84, v90
	v_lshl_add_u64 v[96:97], v[96:97], 0, v[136:137]
	v_mul_f32_e32 v80, v80, v84
	v_mul_f32_e32 v84, v85, v91
	v_mul_f32_e32 v85, 0xbfb8aa3b, v86
	global_store_dwordx2 v[96:97], v[88:89], off
	v_exp_f32_e32 v85, v85
	v_mul_f32_e32 v88, 0xbfb8aa3b, v87
	v_exp_f32_e32 v88, v88
	v_mul_f32_e32 v81, v81, v84
	v_add_f32_e32 v84, 1.0, v85
	v_rcp_f32_e32 v84, v84
	v_add_f32_e32 v85, 1.0, v88
	v_rcp_f32_e32 v85, v85
	v_cvt_pk_bf16_f32 v80, v80, v81
	v_mul_f32_e32 v81, v86, v84
	v_mul_f32_e32 v81, v82, v81
	v_mul_f32_e32 v82, v87, v85
	v_mul_f32_e32 v82, v83, v82
	v_cvt_pk_bf16_f32 v81, v81, v82
	v_mul_f32_e32 v82, 0xbfb8aa3b, v76
	v_exp_f32_e32 v82, v82
	v_mul_f32_e32 v83, 0xbfb8aa3b, v77
	v_exp_f32_e32 v83, v83
	global_store_dwordx2 v[96:97], v[80:81], off offset:128
	v_add_f32_e32 v82, 1.0, v82
	v_rcp_f32_e32 v82, v82
	v_add_f32_e32 v83, 1.0, v83
	v_rcp_f32_e32 v83, v83
	v_or_b32_e32 v80, 48, v151
	v_mul_f32_e32 v76, v76, v82
	v_mul_f32_e32 v72, v72, v76
	v_mul_f32_e32 v76, v77, v83
	v_mul_f32_e32 v77, 0xbfb8aa3b, v78
	v_exp_f32_e32 v77, v77
	v_mul_f32_e32 v82, 0xbfb8aa3b, v79
	v_exp_f32_e32 v82, v82
	v_mul_f32_e32 v73, v73, v76
	v_add_f32_e32 v76, 1.0, v77
	v_rcp_f32_e32 v76, v76
	v_add_f32_e32 v77, 1.0, v82
	v_rcp_f32_e32 v77, v77
	v_cvt_pk_bf16_f32 v72, v72, v73
	v_mul_f32_e32 v73, v78, v76
	v_mul_f32_e32 v73, v74, v73
	v_mul_f32_e32 v74, v79, v77
	v_mul_f32_e32 v74, v75, v74
	v_mul_f32_e32 v75, 0xbfb8aa3b, v68
	v_exp_f32_e32 v75, v75
	v_mul_f32_e32 v76, 0xbfb8aa3b, v69
	v_exp_f32_e32 v76, v76
	v_cvt_pk_bf16_f32 v73, v73, v74
	v_add_f32_e32 v74, 1.0, v75
	v_rcp_f32_e32 v74, v74
	v_add_f32_e32 v75, 1.0, v76
	v_rcp_f32_e32 v75, v75
	v_mad_i64_i32 v[80:81], s[26:27], v80, s55, v[144:145]
	v_lshl_add_u64 v[80:81], v[80:81], 0, s[24:25]
	v_lshl_add_u64 v[80:81], v[80:81], 0, s[12:13]
	v_mul_f32_e32 v68, v68, v74
	v_lshl_add_u64 v[80:81], v[80:81], 0, v[136:137]
	v_mul_f32_e32 v64, v64, v68
	v_mul_f32_e32 v68, v69, v75
	v_mul_f32_e32 v69, 0xbfb8aa3b, v70
	global_store_dwordx2 v[80:81], v[72:73], off
	v_exp_f32_e32 v69, v69
	v_mul_f32_e32 v72, 0xbfb8aa3b, v71
	v_exp_f32_e32 v72, v72
	v_mul_f32_e32 v65, v65, v68
	v_add_f32_e32 v68, 1.0, v69
	v_rcp_f32_e32 v68, v68
	v_add_f32_e32 v69, 1.0, v72
	v_rcp_f32_e32 v69, v69
	v_cvt_pk_bf16_f32 v64, v64, v65
	v_mul_f32_e32 v65, v70, v68
	v_mul_f32_e32 v65, v66, v65
	v_mul_f32_e32 v66, v71, v69
	v_mul_f32_e32 v66, v67, v66
	v_cvt_pk_bf16_f32 v65, v65, v66
	v_mul_f32_e32 v66, 0xbfb8aa3b, v60
	v_exp_f32_e32 v66, v66
	v_mul_f32_e32 v67, 0xbfb8aa3b, v61
	v_exp_f32_e32 v67, v67
	global_store_dwordx2 v[80:81], v[64:65], off offset:128
	v_add_f32_e32 v66, 1.0, v66
	v_rcp_f32_e32 v66, v66
	v_add_f32_e32 v67, 1.0, v67
	v_rcp_f32_e32 v67, v67
	v_add_u32_e32 v64, 0x80, v151
	v_mul_f32_e32 v60, v60, v66
	v_mul_f32_e32 v56, v56, v60
	v_mul_f32_e32 v60, v61, v67
	v_mul_f32_e32 v61, 0xbfb8aa3b, v62
	v_exp_f32_e32 v61, v61
	v_mul_f32_e32 v66, 0xbfb8aa3b, v63
	v_exp_f32_e32 v66, v66
	v_mul_f32_e32 v57, v57, v60
	v_add_f32_e32 v60, 1.0, v61
	v_rcp_f32_e32 v60, v60
	v_add_f32_e32 v61, 1.0, v66
	v_rcp_f32_e32 v61, v61
	v_cvt_pk_bf16_f32 v56, v56, v57
	v_mul_f32_e32 v57, v62, v60
	v_mul_f32_e32 v57, v58, v57
	v_mul_f32_e32 v58, v63, v61
	v_mul_f32_e32 v58, v59, v58
	v_mul_f32_e32 v59, 0xbfb8aa3b, v52
	v_exp_f32_e32 v59, v59
	v_mul_f32_e32 v60, 0xbfb8aa3b, v53
	v_exp_f32_e32 v60, v60
	v_cvt_pk_bf16_f32 v57, v57, v58
	v_add_f32_e32 v58, 1.0, v59
	v_rcp_f32_e32 v58, v58
	v_add_f32_e32 v59, 1.0, v60
	v_rcp_f32_e32 v59, v59
	v_mad_i64_i32 v[64:65], s[26:27], v64, s55, v[144:145]
	v_lshl_add_u64 v[64:65], v[64:65], 0, s[24:25]
	v_lshl_add_u64 v[64:65], v[64:65], 0, s[12:13]
	v_mul_f32_e32 v52, v52, v58
	v_lshl_add_u64 v[64:65], v[64:65], 0, v[136:137]
	v_mul_f32_e32 v48, v48, v52
	v_mul_f32_e32 v52, v53, v59
	v_mul_f32_e32 v53, 0xbfb8aa3b, v54
	global_store_dwordx2 v[64:65], v[56:57], off
	v_exp_f32_e32 v53, v53
	v_mul_f32_e32 v56, 0xbfb8aa3b, v55
	v_exp_f32_e32 v56, v56
	v_mul_f32_e32 v49, v49, v52
	v_add_f32_e32 v52, 1.0, v53
	v_rcp_f32_e32 v52, v52
	v_add_f32_e32 v53, 1.0, v56
	v_rcp_f32_e32 v53, v53
	v_cvt_pk_bf16_f32 v48, v48, v49
	v_mul_f32_e32 v49, v54, v52
	v_mul_f32_e32 v49, v50, v49
	v_mul_f32_e32 v50, v55, v53
	v_mul_f32_e32 v50, v51, v50
	v_cvt_pk_bf16_f32 v49, v49, v50
	v_mul_f32_e32 v50, 0xbfb8aa3b, v44
	v_exp_f32_e32 v50, v50
	v_mul_f32_e32 v51, 0xbfb8aa3b, v45
	v_exp_f32_e32 v51, v51
	global_store_dwordx2 v[64:65], v[48:49], off offset:128
	v_add_f32_e32 v50, 1.0, v50
	v_rcp_f32_e32 v50, v50
	v_add_f32_e32 v51, 1.0, v51
	v_rcp_f32_e32 v51, v51
	v_add_u32_e32 v48, 0x90, v151
	v_mul_f32_e32 v44, v44, v50
	v_mul_f32_e32 v40, v40, v44
	v_mul_f32_e32 v44, v45, v51
	v_mul_f32_e32 v45, 0xbfb8aa3b, v46
	v_exp_f32_e32 v45, v45
	v_mul_f32_e32 v50, 0xbfb8aa3b, v47
	v_exp_f32_e32 v50, v50
	v_mul_f32_e32 v41, v41, v44
	v_add_f32_e32 v44, 1.0, v45
	v_rcp_f32_e32 v44, v44
	v_add_f32_e32 v45, 1.0, v50
	v_rcp_f32_e32 v45, v45
	v_cvt_pk_bf16_f32 v40, v40, v41
	v_mul_f32_e32 v41, v46, v44
	v_mul_f32_e32 v41, v42, v41
	v_mul_f32_e32 v42, v47, v45
	v_mul_f32_e32 v42, v43, v42
	v_mul_f32_e32 v43, 0xbfb8aa3b, v36
	v_exp_f32_e32 v43, v43
	v_mul_f32_e32 v44, 0xbfb8aa3b, v37
	v_exp_f32_e32 v44, v44
	v_cvt_pk_bf16_f32 v41, v41, v42
	v_add_f32_e32 v42, 1.0, v43
	v_rcp_f32_e32 v42, v42
	v_add_f32_e32 v43, 1.0, v44
	v_rcp_f32_e32 v43, v43
	v_mad_i64_i32 v[48:49], s[26:27], v48, s55, v[144:145]
	v_lshl_add_u64 v[48:49], v[48:49], 0, s[24:25]
	v_lshl_add_u64 v[48:49], v[48:49], 0, s[12:13]
	v_mul_f32_e32 v36, v36, v42
	v_lshl_add_u64 v[48:49], v[48:49], 0, v[136:137]
	v_mul_f32_e32 v32, v32, v36
	v_mul_f32_e32 v36, v37, v43
	v_mul_f32_e32 v37, 0xbfb8aa3b, v38
	global_store_dwordx2 v[48:49], v[40:41], off
	v_exp_f32_e32 v37, v37
	v_mul_f32_e32 v40, 0xbfb8aa3b, v39
	v_exp_f32_e32 v40, v40
	v_mul_f32_e32 v33, v33, v36
	v_add_f32_e32 v36, 1.0, v37
	v_rcp_f32_e32 v36, v36
	v_add_f32_e32 v37, 1.0, v40
	v_rcp_f32_e32 v37, v37
	v_cvt_pk_bf16_f32 v32, v32, v33
	v_mul_f32_e32 v33, v38, v36
	v_mul_f32_e32 v33, v34, v33
	v_mul_f32_e32 v34, v39, v37
	v_mul_f32_e32 v34, v35, v34
	v_cvt_pk_bf16_f32 v33, v33, v34
	v_mul_f32_e32 v34, 0xbfb8aa3b, v28
	v_exp_f32_e32 v34, v34
	v_mul_f32_e32 v35, 0xbfb8aa3b, v29
	v_exp_f32_e32 v35, v35
	global_store_dwordx2 v[48:49], v[32:33], off offset:128
	v_add_f32_e32 v34, 1.0, v34
	v_rcp_f32_e32 v34, v34
	v_add_f32_e32 v35, 1.0, v35
	v_rcp_f32_e32 v35, v35
	v_add_u32_e32 v32, 0xa0, v151
	v_mul_f32_e32 v28, v28, v34
	v_mul_f32_e32 v24, v24, v28
	v_mul_f32_e32 v28, v29, v35
	v_mul_f32_e32 v29, 0xbfb8aa3b, v30
	v_exp_f32_e32 v29, v29
	v_mul_f32_e32 v34, 0xbfb8aa3b, v31
	v_exp_f32_e32 v34, v34
	v_mul_f32_e32 v25, v25, v28
	v_add_f32_e32 v28, 1.0, v29
	v_rcp_f32_e32 v28, v28
	v_add_f32_e32 v29, 1.0, v34
	v_rcp_f32_e32 v29, v29
	v_cvt_pk_bf16_f32 v24, v24, v25
	v_mul_f32_e32 v25, v30, v28
	v_mul_f32_e32 v25, v26, v25
	v_mul_f32_e32 v26, v31, v29
	v_mul_f32_e32 v26, v27, v26
	v_mul_f32_e32 v27, 0xbfb8aa3b, v20
	v_exp_f32_e32 v27, v27
	v_mul_f32_e32 v28, 0xbfb8aa3b, v21
	v_exp_f32_e32 v28, v28
	v_cvt_pk_bf16_f32 v25, v25, v26
	v_add_f32_e32 v26, 1.0, v27
	v_rcp_f32_e32 v26, v26
	v_add_f32_e32 v27, 1.0, v28
	v_rcp_f32_e32 v27, v27
	v_mad_i64_i32 v[32:33], s[26:27], v32, s55, v[144:145]
	v_lshl_add_u64 v[32:33], v[32:33], 0, s[24:25]
	v_lshl_add_u64 v[32:33], v[32:33], 0, s[12:13]
	v_mul_f32_e32 v20, v20, v26
	v_lshl_add_u64 v[32:33], v[32:33], 0, v[136:137]
	v_mul_f32_e32 v16, v16, v20
	v_mul_f32_e32 v20, v21, v27
	v_mul_f32_e32 v21, 0xbfb8aa3b, v22
	global_store_dwordx2 v[32:33], v[24:25], off
	v_exp_f32_e32 v21, v21
	v_mul_f32_e32 v24, 0xbfb8aa3b, v23
	v_exp_f32_e32 v24, v24
	v_mul_f32_e32 v17, v17, v20
	v_add_f32_e32 v20, 1.0, v21
	v_rcp_f32_e32 v20, v20
	v_add_f32_e32 v21, 1.0, v24
	v_rcp_f32_e32 v21, v21
	v_cvt_pk_bf16_f32 v16, v16, v17
	v_mul_f32_e32 v17, v22, v20
	v_mul_f32_e32 v17, v18, v17
	v_mul_f32_e32 v18, v23, v21
	v_mul_f32_e32 v18, v19, v18
	v_cvt_pk_bf16_f32 v17, v17, v18
	v_mul_f32_e32 v18, 0xbfb8aa3b, v12
	v_exp_f32_e32 v18, v18
	v_mul_f32_e32 v19, 0xbfb8aa3b, v13
	v_exp_f32_e32 v19, v19
	global_store_dwordx2 v[32:33], v[16:17], off offset:128
	v_add_f32_e32 v18, 1.0, v18
	v_rcp_f32_e32 v18, v18
	v_add_f32_e32 v19, 1.0, v19
	v_rcp_f32_e32 v19, v19
	v_add_u32_e32 v16, 0xb0, v151
	v_mul_f32_e32 v12, v12, v18
	v_mul_f32_e32 v8, v8, v12
	v_mul_f32_e32 v12, v13, v19
	v_mul_f32_e32 v13, 0xbfb8aa3b, v14
	v_exp_f32_e32 v13, v13
	v_mul_f32_e32 v18, 0xbfb8aa3b, v15
	v_exp_f32_e32 v18, v18
	v_mul_f32_e32 v9, v9, v12
	v_add_f32_e32 v12, 1.0, v13
	v_rcp_f32_e32 v12, v12
	v_add_f32_e32 v13, 1.0, v18
	v_rcp_f32_e32 v13, v13
	v_cvt_pk_bf16_f32 v8, v8, v9
	v_mul_f32_e32 v9, v14, v12
	v_mul_f32_e32 v9, v10, v9
	v_mul_f32_e32 v10, v15, v13
	v_mul_f32_e32 v10, v11, v10
	v_mul_f32_e32 v11, 0xbfb8aa3b, v4
	v_exp_f32_e32 v11, v11
	v_mul_f32_e32 v12, 0xbfb8aa3b, v5
	v_exp_f32_e32 v12, v12
	v_cvt_pk_bf16_f32 v9, v9, v10
	v_add_f32_e32 v10, 1.0, v11
	v_rcp_f32_e32 v10, v10
	v_add_f32_e32 v11, 1.0, v12
	v_rcp_f32_e32 v11, v11
	v_mad_i64_i32 v[16:17], s[26:27], v16, s55, v[144:145]
	v_lshl_add_u64 v[16:17], v[16:17], 0, s[24:25]
	v_lshl_add_u64 v[16:17], v[16:17], 0, s[12:13]
	v_mul_f32_e32 v4, v4, v10
	v_lshl_add_u64 v[16:17], v[16:17], 0, v[136:137]
	v_mul_f32_e32 v0, v0, v4
	v_mul_f32_e32 v4, v5, v11
	v_mul_f32_e32 v5, 0xbfb8aa3b, v6
	global_store_dwordx2 v[16:17], v[8:9], off
	v_exp_f32_e32 v5, v5
	v_mul_f32_e32 v8, 0xbfb8aa3b, v7
	v_exp_f32_e32 v8, v8
	v_mul_f32_e32 v1, v1, v4
	v_add_f32_e32 v4, 1.0, v5
	v_rcp_f32_e32 v4, v4
	v_add_f32_e32 v5, 1.0, v8
	v_rcp_f32_e32 v5, v5
	v_cvt_pk_bf16_f32 v0, v0, v1
	v_mul_f32_e32 v1, v6, v4
	v_mul_f32_e32 v1, v2, v1
	v_mul_f32_e32 v2, v7, v5
	s_and_b64 vcc, exec, s[18:19]
	s_mov_b32 s13, s16
	s_mov_b32 s24, s14
	s_mov_b64 s[28:29], s[22:23]
	s_mov_b64 s[26:27], s[20:21]
	v_mul_f32_e32 v2, v3, v2
	v_cvt_pk_bf16_f32 v1, v1, v2
	global_store_dwordx2 v[16:17], v[0:1], off offset:128
	s_cbranch_vccz .LBB0_1062
	s_waitcnt vmcnt(0)
	s_cmpk_gt_u32 s2, 0xff
	s_cbranch_scc1 .LBB0_1069
	s_barrier
